# E48: W1/W2 weight conversion moved from PREP into the idle work-groups of the G1 GEMM last partial round (hand-written pipelined transpose-convert)
# speedup vs baseline: 1.0152x; 1.0031x over previous
; #define P (*get_params())
; __global__ void __launch_bounds__(512) fwd_megakernel(Params Parg) {
;     ...
;       conv_matrix(P.mlp_w1 + (size_t)l * 1024 * 4096, 1024, 4096, 4096, W1, nullptr, tile);
;       conv_matrix(P.mlp_w2 + (size_t)l * 4096 * 1024, 4096, 1024, 1024, W2, nullptr, tile);
;       norm_phase(X, HB, P.norm_w + (size_t)(l * 2 + 0) * 1024, modL, modC, 0, 1024, PART, l > 0 ? 8 : 0, l == 0 ? P.x : nullptr, l == 0 ? P.ctx : nullptr);
.LBB0_419:
	v_readlane_b32 s14, v254, 10
	v_readlane_b32 s15, v254, 11
	s_lshl_b64 s[4:5], s[44:45], 24
	s_mov_b64 s[10:11], s[0:1]
	v_cndmask_b32_e64 v1, 0, 1, s[14:15]
	s_mov_b64 s[8:9], s[0:1]
	v_mov_b32_e32 v0, v187
	v_cmp_ne_u32_e64 s[6:7], 1, v1
	s_andn2_b64 vcc, exec, s[14:15]
.LBB0_470:
	s_mov_b64 s[10:11], s[0:1]
	s_mov_b64 s[8:9], s[0:1]
	v_mov_b32_e32 v0, v187
	s_and_b64 vcc, exec, s[6:7]
.LBB0_521:
	s_mov_b64 s[6:7], s[0:1]
	s_load_dwordx2 s[8:9], s[6:7], 0xd8
	s_mov_b64 s[6:7], s[0:1]
	s_mov_b64 s[10:11], s[0:1]
	s_load_dwordx2 s[6:7], s[6:7], 0xd8
	s_load_dwordx2 s[22:23], s[10:11], 0x30
	s_mov_b64 s[10:11], s[0:1]
	s_load_dwordx2 s[20:21], s[10:11], 0xd8
	s_mov_b64 s[10:11], s[0:1]
	s_load_dwordx2 s[18:19], s[10:11], 0xd8
	s_mov_b64 s[10:11], s[0:1]
	s_load_dwordx2 s[26:27], s[10:11], 0xd8
	s_cmp_lg_u32 s44, 0
	s_cselect_b64 s[4:5], -1, 0
	s_cmp_eq_u32 s44, 0
	s_cselect_b64 s[16:17], -1, 0
	s_mov_b64 s[10:11], 0
	s_and_b64 vcc, exec, s[4:5]
	s_mov_b64 s[14:15], 0
	s_cbranch_vccnz .LBB0_523
	s_mov_b64 s[14:15], s[0:1]
	s_load_dwordx2 s[14:15], s[14:15], 0x0

; __device__ __forceinline__ int tid_() { int t = threadIdx.x; asm volatile("" : "+v"(t)); return t; }
; __device__ __forceinline__ void conv_matrix(const float* __restrict__ src, int K, int N, int Npad, bf16_t* __restrict__ dst, const float* __restrict__ scale, float* tile) {
;   const int nk = K / 64, nn = Npad / 64, tot = nk * nn;
;   const int tid = tid_(), tx = tid & 63, ty = tid >> 6, nl = tid >> 3, ks = (tid & 7) * 8;
;   for (int i0 = blockIdx.x; i0 < tot; i0 += 2 * gridDim.x) {
;     const int i1 = i0 + gridDim.x; const bool has1 = i1 < tot;
;     const int k0a = (i0 % nk) * 64, n0a = (i0 / nk) * 64, k0b = has1 ? (i1 % nk) * 64 : 0, n0b = has1 ? (i1 / nk) * 64 : 0;
;     float va[8], vb[8];
; #pragma unroll
;     for (int i = 0; i < 8; ++i) { const int k = k0a + ty + 8 * i, n = n0a + tx; float v = (n < N) ? src[(size_t)k * N + n] : 0.f; if (scale) v *= scale[k]; va[i] = v; }
;     if (has1) {
; #pragma unroll
;       for (int i = 0; i < 8; ++i) { const int k = k0b + ty + 8 * i, n = n0b + tx; float v = (n < N) ? src[(size_t)k * N + n] : 0.f; if (scale) v *= scale[k]; vb[i] = v; }
;     }
.LBB0_1028:
	s_cmp_lt_u32 s2, 12
	s_cbranch_scc1 .Lcvo_skip
	v_writelane_b32 v255, s4, 46
	v_writelane_b32 v255, s5, 47
	v_writelane_b32 v255, s10, 48
	v_writelane_b32 v255, s11, 49
	v_writelane_b32 v255, s12, 50
	v_writelane_b32 v255, s13, 51
	v_writelane_b32 v255, s14, 52
	v_writelane_b32 v255, s15, 53
	v_writelane_b32 v255, s20, 54
	v_writelane_b32 v255, s21, 55
	v_writelane_b32 v255, s22, 56
	v_writelane_b32 v255, s23, 57
	v_writelane_b32 v255, s24, 58
	v_writelane_b32 v255, s25, 59
	v_writelane_b32 v255, s26, 60
	v_writelane_b32 v255, s27, 61
	s_load_dwordx2 s[10:11], s[0:1], 0x40
	s_load_dwordx2 s[12:13], s[0:1], 0x48
	s_load_dwordx2 s[14:15], s[0:1], 0xd8
	v_and_b32_e32 v1, 63, v187
	v_lshrrev_b32_e32 v7, 6, v187
	v_lshrrev_b32_e32 v4, 3, v187
	v_and_b32_e32 v5, 7, v187
	s_nop 1
	v_readfirstlane_b32 s6, v7
	v_readlane_b32 s7, v255, 32
	v_mul_u32_u24_e32 v2, 0x41, v7
	v_add_u32_e32 v2, v2, v1
	v_lshlrev_b32_e32 v2, 2, v2
	v_add_u32_e32 v2, 16, v2
	v_lshlrev_b32_e32 v1, 2, v1
	v_mul_u32_u24_e32 v3, 0x208, v5
	v_add_u32_e32 v3, v3, v4
	v_lshlrev_b32_e32 v3, 2, v3
	v_add_u32_e32 v3, 16, v3
	v_lshlrev_b32_e32 v5, 4, v5
	s_lshl_b32 s7, s7, 24
	s_waitcnt lgkmcnt(0)
	s_add_u32 s10, s10, s7
	s_addc_u32 s11, s11, 0
	s_add_u32 s12, s12, s7
	s_addc_u32 s13, s13, 0
	s_sub_u32 s4, s2, 12
	s_cmp_lt_u32 s4, 0x400
	s_cselect_b32 s20, 4, 6
	s_cselect_b32 s21, 14, 12
	s_cselect_b32 s26, s10, s12
	s_cselect_b32 s27, s11, s13
	s_and_b32 s22, s4, 0x3ff
	s_lshl_b32 s25, 1, s20
	s_sub_u32 s25, s25, 1
	s_and_b32 s23, s22, s25
	s_lshr_b32 s24, s22, s20
	s_lshl_b32 s23, s23, 6
	s_add_u32 s23, s23, s6
	s_lshl_b32 s23, s23, s21
	s_lshl_b32 s24, s24, 8
	s_add_u32 s23, s23, s24
	s_add_u32 s26, s26, s23
	s_addc_u32 s27, s27, 0
	s_add_u32 s25, s21, 3
	s_lshl_b32 s25, 1, s25
	v_add_u32_e32 v21, s25, v1
	v_add_u32_e32 v22, s25, v21
	v_add_u32_e32 v23, s25, v22
	v_add_u32_e32 v24, s25, v23
	v_add_u32_e32 v25, s25, v24
	v_add_u32_e32 v26, s25, v25
	v_add_u32_e32 v27, s25, v26
	global_load_dword v30, v1, s[26:27]
	global_load_dword v31, v21, s[26:27]
	global_load_dword v32, v22, s[26:27]
	global_load_dword v33, v23, s[26:27]
	global_load_dword v34, v24, s[26:27]
	global_load_dword v35, v25, s[26:27]
	global_load_dword v36, v26, s[26:27]
	global_load_dword v37, v27, s[26:27]
	s_mov_b32 s7, 1
.Lcvo_loop:
	s_add_u32 s5, s4, 244
	s_cmp_lt_u32 s5, 0x800
	s_cbranch_scc0 .Lcvo_lastA
	s_cmp_lt_u32 s5, 0x400
	s_cselect_b32 s20, 4, 6
	s_cselect_b32 s21, 14, 12
	s_cselect_b32 s26, s10, s12
	s_cselect_b32 s27, s11, s13
	s_and_b32 s22, s5, 0x3ff
	s_lshl_b32 s25, 1, s20
	s_sub_u32 s25, s25, 1
	s_and_b32 s23, s22, s25
	s_lshr_b32 s24, s22, s20
	s_lshl_b32 s23, s23, 6
	s_add_u32 s23, s23, s6
	s_lshl_b32 s23, s23, s21
	s_lshl_b32 s24, s24, 8
	s_add_u32 s23, s23, s24
	s_add_u32 s26, s26, s23
	s_addc_u32 s27, s27, 0
	s_add_u32 s25, s21, 3
	s_lshl_b32 s25, 1, s25
	v_add_u32_e32 v21, s25, v1
	v_add_u32_e32 v22, s25, v21
	v_add_u32_e32 v23, s25, v22
	v_add_u32_e32 v24, s25, v23
	v_add_u32_e32 v25, s25, v24
	v_add_u32_e32 v26, s25, v25
	v_add_u32_e32 v27, s25, v26
	global_load_dword v40, v1, s[26:27]
	global_load_dword v41, v21, s[26:27]
	global_load_dword v42, v22, s[26:27]
	global_load_dword v43, v23, s[26:27]
	global_load_dword v44, v24, s[26:27]
	global_load_dword v45, v25, s[26:27]
	global_load_dword v46, v26, s[26:27]
	global_load_dword v47, v27, s[26:27]
	s_cmp_eq_u32 s7, 1
	s_cbranch_scc1 .Lcvo_wA8
	s_waitcnt vmcnt(9)
	s_branch .Lcvo_pA
.Lcvo_wA8:
	s_waitcnt vmcnt(8)
; __device__ __forceinline__ unsigned cvt_pk_bf16(float lo, float hi) { unsigned r; asm volatile("v_cvt_pk_bf16_f32 %0, %1, %2" : "=v"(r) : "v"(lo), "v"(hi)); return r; }
; __device__ __forceinline__ void conv_matrix(const float* __restrict__ src, int K, int N, int Npad, bf16_t* __restrict__ dst, const float* __restrict__ scale, float* tile) {
;     ...
;     __syncthreads();
; #pragma unroll
;     for (int i = 0; i < 8; ++i) { tile[(ty + 8 * i) * 65 + tx] = va[i]; if (has1) tile[4160 + (ty + 8 * i) * 65 + tx] = vb[i]; }
;     __syncthreads();
;     { float v[8];
; #pragma unroll
;       for (int j = 0; j < 8; ++j) v[j] = tile[(ks + j) * 65 + nl];
;       u32x4 w = {cvt_pk_bf16(v[0], v[1]), cvt_pk_bf16(v[2], v[3]), cvt_pk_bf16(v[4], v[5]), cvt_pk_bf16(v[6], v[7])};
;       *(u32x4*)(dst + (size_t)(n0a + nl) * K + k0a + ks) = w; }
;     if (has1) { float v[8];
; #pragma unroll
;       for (int j = 0; j < 8; ++j) v[j] = tile[4160 + (ks + j) * 65 + nl];
;       u32x4 w = {cvt_pk_bf16(v[0], v[1]), cvt_pk_bf16(v[2], v[3]), cvt_pk_bf16(v[4], v[5]), cvt_pk_bf16(v[6], v[7])};
;       *(u32x4*)(dst + (size_t)(n0b + nl) * K + k0b + ks) = w; }
.Lcvo_pA:
	s_mov_b32 s7, 0
	ds_write_b32 v2, v30 offset:0
	ds_write_b32 v2, v31 offset:2080
	ds_write_b32 v2, v32 offset:4160
	ds_write_b32 v2, v33 offset:6240
	ds_write_b32 v2, v34 offset:8320
	ds_write_b32 v2, v35 offset:10400
	ds_write_b32 v2, v36 offset:12480
	ds_write_b32 v2, v37 offset:14560
	s_cmp_lt_u32 s4, 0x400
	s_cselect_b32 s20, 4, 6
	s_cselect_b32 s21, 17, 19
	s_cselect_b32 s8, 11, 13
	s_mov_b32 s9, 0x9280000
	s_cselect_b32 s9, 0x8a80000, s9
	s_and_b32 s22, s4, 0x3ff
	s_lshl_b32 s25, 1, s20
	s_sub_u32 s25, s25, 1
	s_and_b32 s23, s22, s25
	s_lshr_b32 s24, s22, s20
	s_lshl_b32 s24, s24, s21
	s_lshl_b32 s23, s23, 7
	s_add_u32 s24, s24, s23
	s_add_u32 s24, s24, s9
	s_add_u32 s26, s14, s24
	s_addc_u32 s27, s15, 0
	v_lshlrev_b32_e32 v6, s8, v4
	v_add_u32_e32 v6, v6, v5
	s_waitcnt lgkmcnt(0)
	s_barrier
	ds_read_b32 v50, v3 offset:0
	ds_read_b32 v51, v3 offset:260
	ds_read_b32 v52, v3 offset:520
	ds_read_b32 v53, v3 offset:780
	ds_read_b32 v54, v3 offset:1040
	ds_read_b32 v55, v3 offset:1300
	ds_read_b32 v56, v3 offset:1560
	ds_read_b32 v57, v3 offset:1820
	s_waitcnt lgkmcnt(0)
	v_cvt_pk_bf16_f32 v60, v50, v51
	v_cvt_pk_bf16_f32 v61, v52, v53
	v_cvt_pk_bf16_f32 v62, v54, v55
	v_cvt_pk_bf16_f32 v63, v56, v57
	global_store_dwordx4 v6, v[60:63], s[26:27]
	s_mov_b32 s4, s5
	s_add_u32 s5, s4, 244
	s_cmp_lt_u32 s5, 0x800
	s_cbranch_scc0 .Lcvo_lastB
	s_cmp_lt_u32 s5, 0x400
	s_cselect_b32 s20, 4, 6
	s_cselect_b32 s21, 14, 12
	s_cselect_b32 s26, s10, s12
	s_cselect_b32 s27, s11, s13
	s_and_b32 s22, s5, 0x3ff
	s_lshl_b32 s25, 1, s20
	s_sub_u32 s25, s25, 1
	s_and_b32 s23, s22, s25
	s_lshr_b32 s24, s22, s20
	s_lshl_b32 s23, s23, 6
	s_add_u32 s23, s23, s6
	s_lshl_b32 s23, s23, s21
	s_lshl_b32 s24, s24, 8
	s_add_u32 s23, s23, s24
	s_add_u32 s26, s26, s23
	s_addc_u32 s27, s27, 0
	s_add_u32 s25, s21, 3
	s_lshl_b32 s25, 1, s25
	v_add_u32_e32 v21, s25, v1
	v_add_u32_e32 v22, s25, v21
	v_add_u32_e32 v23, s25, v22
	v_add_u32_e32 v24, s25, v23
	v_add_u32_e32 v25, s25, v24
	v_add_u32_e32 v26, s25, v25
	v_add_u32_e32 v27, s25, v26
	global_load_dword v30, v1, s[26:27]
	global_load_dword v31, v21, s[26:27]
	global_load_dword v32, v22, s[26:27]
	global_load_dword v33, v23, s[26:27]
	global_load_dword v34, v24, s[26:27]
	global_load_dword v35, v25, s[26:27]
	global_load_dword v36, v26, s[26:27]
	global_load_dword v37, v27, s[26:27]
	s_waitcnt vmcnt(9)
	ds_write_b32 v2, v40 offset:16640
	ds_write_b32 v2, v41 offset:18720
	ds_write_b32 v2, v42 offset:20800
	ds_write_b32 v2, v43 offset:22880
	ds_write_b32 v2, v44 offset:24960
	ds_write_b32 v2, v45 offset:27040
	ds_write_b32 v2, v46 offset:29120
	ds_write_b32 v2, v47 offset:31200
	s_cmp_lt_u32 s4, 0x400
	s_cselect_b32 s20, 4, 6
	s_cselect_b32 s21, 17, 19
	s_cselect_b32 s8, 11, 13
	s_mov_b32 s9, 0x9280000
	s_cselect_b32 s9, 0x8a80000, s9
	s_and_b32 s22, s4, 0x3ff
	s_lshl_b32 s25, 1, s20
	s_sub_u32 s25, s25, 1
	s_and_b32 s23, s22, s25
	s_lshr_b32 s24, s22, s20
	s_lshl_b32 s24, s24, s21
	s_lshl_b32 s23, s23, 7
	s_add_u32 s24, s24, s23
	s_add_u32 s24, s24, s9
	s_add_u32 s26, s14, s24
	s_addc_u32 s27, s15, 0
	v_lshlrev_b32_e32 v6, s8, v4
	v_add_u32_e32 v6, v6, v5
	s_waitcnt lgkmcnt(0)
	s_barrier
	ds_read_b32 v50, v3 offset:16640
	ds_read_b32 v51, v3 offset:16900
	ds_read_b32 v52, v3 offset:17160
	ds_read_b32 v53, v3 offset:17420
	ds_read_b32 v54, v3 offset:17680
	ds_read_b32 v55, v3 offset:17940
	ds_read_b32 v56, v3 offset:18200
	ds_read_b32 v57, v3 offset:18460
	s_waitcnt lgkmcnt(0)
	v_cvt_pk_bf16_f32 v60, v50, v51
	v_cvt_pk_bf16_f32 v61, v52, v53
	v_cvt_pk_bf16_f32 v62, v54, v55
	v_cvt_pk_bf16_f32 v63, v56, v57
	global_store_dwordx4 v6, v[60:63], s[26:27]
	s_mov_b32 s4, s5
	s_branch .Lcvo_loop
.Lcvo_lastA:
	s_waitcnt vmcnt(0)
	ds_write_b32 v2, v30 offset:0
	ds_write_b32 v2, v31 offset:2080
	ds_write_b32 v2, v32 offset:4160
	ds_write_b32 v2, v33 offset:6240
	ds_write_b32 v2, v34 offset:8320
	ds_write_b32 v2, v35 offset:10400
	ds_write_b32 v2, v36 offset:12480
	ds_write_b32 v2, v37 offset:14560
	s_cmp_lt_u32 s4, 0x400
	s_cselect_b32 s20, 4, 6
	s_cselect_b32 s21, 17, 19
	s_cselect_b32 s8, 11, 13
	s_mov_b32 s9, 0x9280000
	s_cselect_b32 s9, 0x8a80000, s9
	s_and_b32 s22, s4, 0x3ff
	s_lshl_b32 s25, 1, s20
	s_sub_u32 s25, s25, 1
	s_and_b32 s23, s22, s25
	s_lshr_b32 s24, s22, s20
	s_lshl_b32 s24, s24, s21
	s_lshl_b32 s23, s23, 7
	s_add_u32 s24, s24, s23
	s_add_u32 s24, s24, s9
	s_add_u32 s26, s14, s24
	s_addc_u32 s27, s15, 0
	v_lshlrev_b32_e32 v6, s8, v4
	v_add_u32_e32 v6, v6, v5
	s_waitcnt lgkmcnt(0)
	s_barrier
	ds_read_b32 v50, v3 offset:0
	ds_read_b32 v51, v3 offset:260
	ds_read_b32 v52, v3 offset:520
	ds_read_b32 v53, v3 offset:780
	ds_read_b32 v54, v3 offset:1040
	ds_read_b32 v55, v3 offset:1300
	ds_read_b32 v56, v3 offset:1560
	ds_read_b32 v57, v3 offset:1820
	s_waitcnt lgkmcnt(0)
	v_cvt_pk_bf16_f32 v60, v50, v51
	v_cvt_pk_bf16_f32 v61, v52, v53
	v_cvt_pk_bf16_f32 v62, v54, v55
	v_cvt_pk_bf16_f32 v63, v56, v57
	global_store_dwordx4 v6, v[60:63], s[26:27]
	s_branch .Lcvo_done
.Lcvo_lastB:
	s_waitcnt vmcnt(0)
	ds_write_b32 v2, v40 offset:16640
	ds_write_b32 v2, v41 offset:18720
	ds_write_b32 v2, v42 offset:20800
	ds_write_b32 v2, v43 offset:22880
	ds_write_b32 v2, v44 offset:24960
	ds_write_b32 v2, v45 offset:27040
	ds_write_b32 v2, v46 offset:29120
	ds_write_b32 v2, v47 offset:31200
	s_cmp_lt_u32 s4, 0x400
	s_cselect_b32 s20, 4, 6
	s_cselect_b32 s21, 17, 19
	s_cselect_b32 s8, 11, 13
	s_mov_b32 s9, 0x9280000
	s_cselect_b32 s9, 0x8a80000, s9
	s_and_b32 s22, s4, 0x3ff
	s_lshl_b32 s25, 1, s20
	s_sub_u32 s25, s25, 1
	s_and_b32 s23, s22, s25
	s_lshr_b32 s24, s22, s20
	s_lshl_b32 s24, s24, s21
	s_lshl_b32 s23, s23, 7
	s_add_u32 s24, s24, s23
	s_add_u32 s24, s24, s9
	s_add_u32 s26, s14, s24
	s_addc_u32 s27, s15, 0
	v_lshlrev_b32_e32 v6, s8, v4
	v_add_u32_e32 v6, v6, v5
	s_waitcnt lgkmcnt(0)
	s_barrier
	ds_read_b32 v50, v3 offset:16640
	ds_read_b32 v51, v3 offset:16900
	ds_read_b32 v52, v3 offset:17160
	ds_read_b32 v53, v3 offset:17420
	ds_read_b32 v54, v3 offset:17680
	ds_read_b32 v55, v3 offset:17940
	ds_read_b32 v56, v3 offset:18200
	ds_read_b32 v57, v3 offset:18460
	s_waitcnt lgkmcnt(0)
	v_cvt_pk_bf16_f32 v60, v50, v51
	v_cvt_pk_bf16_f32 v61, v52, v53
	v_cvt_pk_bf16_f32 v62, v54, v55
	v_cvt_pk_bf16_f32 v63, v56, v57
	global_store_dwordx4 v6, v[60:63], s[26:27]
.Lcvo_done:
	s_nop 1
	v_readlane_b32 s4, v255, 46
	v_readlane_b32 s5, v255, 47
	v_readlane_b32 s10, v255, 48
	v_readlane_b32 s11, v255, 49
	v_readlane_b32 s12, v255, 50
	v_readlane_b32 s13, v255, 51
	v_readlane_b32 s14, v255, 52
	v_readlane_b32 s15, v255, 53
	v_readlane_b32 s20, v255, 54
	v_readlane_b32 s21, v255, 55
	v_readlane_b32 s22, v255, 56
	v_readlane_b32 s23, v255, 57
	v_readlane_b32 s24, v255, 58
	v_readlane_b32 s25, v255, 59
	v_readlane_b32 s26, v255, 60
	v_readlane_b32 s27, v255, 61

; __device__ __forceinline__ int tid_() { int t = threadIdx.x; asm volatile("" : "+v"(t)); return t; }
; __device__ __forceinline__ void conv_matrix(const float* __restrict__ src, int K, int N, int Npad, bf16_t* __restrict__ dst, const float* __restrict__ scale, float* tile) {
;   const int nk = K / 64, nn = Npad / 64, tot = nk * nn;
;   const int tid = tid_(), tx = tid & 63, ty = tid >> 6, nl = tid >> 3, ks = (tid & 7) * 8;
;   for (int i0 = blockIdx.x; i0 < tot; i0 += 2 * gridDim.x) {
;     const int i1 = i0 + gridDim.x; const bool has1 = i1 < tot;
;     const int k0a = (i0 % nk) * 64, n0a = (i0 / nk) * 64, k0b = has1 ? (i1 % nk) * 64 : 0, n0b = has1 ? (i1 / nk) * 64 : 0;
;     float va[8], vb[8];
; #pragma unroll
;     for (int i = 0; i < 8; ++i) { const int k = k0a + ty + 8 * i, n = n0a + tx; float v = (n < N) ? src[(size_t)k * N + n] : 0.f; if (scale) v *= scale[k]; va[i] = v; }
;     if (has1) {
; #pragma unroll
;       for (int i = 0; i < 8; ++i) { const int k = k0b + ty + 8 * i, n = n0b + tx; float v = (n < N) ? src[(size_t)k * N + n] : 0.f; if (scale) v *= scale[k]; vb[i] = v; }
;     }
.LBB0_2057:
	s_cmp_lt_u32 s2, 77
	s_cbranch_scc1 .Lcve_skip
	v_writelane_b32 v255, s4, 46
	v_writelane_b32 v255, s5, 47
	v_writelane_b32 v255, s10, 48
	v_writelane_b32 v255, s11, 49
	v_writelane_b32 v255, s12, 50
	v_writelane_b32 v255, s13, 51
	v_writelane_b32 v255, s14, 52
	v_writelane_b32 v255, s15, 53
	v_writelane_b32 v255, s20, 54
	v_writelane_b32 v255, s21, 55
	v_writelane_b32 v255, s22, 56
	v_writelane_b32 v255, s23, 57
	v_writelane_b32 v255, s24, 58
	v_writelane_b32 v255, s25, 59
	v_writelane_b32 v255, s26, 60
	v_writelane_b32 v255, s27, 61
	s_load_dwordx2 s[10:11], s[0:1], 0x40
	s_load_dwordx2 s[12:13], s[0:1], 0x48
	s_load_dwordx2 s[14:15], s[0:1], 0xd8
	v_and_b32_e32 v1, 63, v187
	v_lshrrev_b32_e32 v7, 6, v187
	v_lshrrev_b32_e32 v4, 3, v187
	v_and_b32_e32 v5, 7, v187
	s_nop 1
	v_readfirstlane_b32 s6, v7
	v_readlane_b32 s7, v255, 32
	v_mul_u32_u24_e32 v2, 0x41, v7
	v_add_u32_e32 v2, v2, v1
	v_lshlrev_b32_e32 v2, 2, v2
	v_add_u32_e32 v2, 16, v2
	v_lshlrev_b32_e32 v1, 2, v1
	v_mul_u32_u24_e32 v3, 0x208, v5
	v_add_u32_e32 v3, v3, v4
	v_lshlrev_b32_e32 v3, 2, v3
	v_add_u32_e32 v3, 16, v3
	v_lshlrev_b32_e32 v5, 4, v5
	s_lshl_b32 s7, s7, 24
	s_waitcnt lgkmcnt(0)
	s_add_u32 s10, s10, s7
	s_addc_u32 s11, s11, 0
	s_add_u32 s12, s12, s7
	s_addc_u32 s13, s13, 0
	s_sub_u32 s4, s2, 77
	s_cmp_lt_u32 s4, 0x400
	s_cselect_b32 s20, 4, 6
	s_cselect_b32 s21, 14, 12
	s_cselect_b32 s26, s10, s12
	s_cselect_b32 s27, s11, s13
	s_and_b32 s22, s4, 0x3ff
	s_lshl_b32 s25, 1, s20
	s_sub_u32 s25, s25, 1
	s_and_b32 s23, s22, s25
	s_lshr_b32 s24, s22, s20
	s_lshl_b32 s23, s23, 6
	s_add_u32 s23, s23, s6
	s_lshl_b32 s23, s23, s21
	s_lshl_b32 s24, s24, 8
	s_add_u32 s23, s23, s24
	s_add_u32 s26, s26, s23
	s_addc_u32 s27, s27, 0
	s_add_u32 s25, s21, 3
	s_lshl_b32 s25, 1, s25
	v_add_u32_e32 v21, s25, v1
	v_add_u32_e32 v22, s25, v21
	v_add_u32_e32 v23, s25, v22
	v_add_u32_e32 v24, s25, v23
	v_add_u32_e32 v25, s25, v24
	v_add_u32_e32 v26, s25, v25
	v_add_u32_e32 v27, s25, v26
	global_load_dword v30, v1, s[26:27]
	global_load_dword v31, v21, s[26:27]
	global_load_dword v32, v22, s[26:27]
	global_load_dword v33, v23, s[26:27]
	global_load_dword v34, v24, s[26:27]
	global_load_dword v35, v25, s[26:27]
	global_load_dword v36, v26, s[26:27]
	global_load_dword v37, v27, s[26:27]
	s_mov_b32 s7, 1
.Lcve_loop:
	s_add_u32 s5, s4, 179
	s_cmp_lt_u32 s5, 0x800
	s_cbranch_scc0 .Lcve_lastA
	s_cmp_lt_u32 s5, 0x400
	s_cselect_b32 s20, 4, 6
	s_cselect_b32 s21, 14, 12
	s_cselect_b32 s26, s10, s12
	s_cselect_b32 s27, s11, s13
	s_and_b32 s22, s5, 0x3ff
	s_lshl_b32 s25, 1, s20
	s_sub_u32 s25, s25, 1
	s_and_b32 s23, s22, s25
	s_lshr_b32 s24, s22, s20
	s_lshl_b32 s23, s23, 6
	s_add_u32 s23, s23, s6
	s_lshl_b32 s23, s23, s21
	s_lshl_b32 s24, s24, 8
	s_add_u32 s23, s23, s24
	s_add_u32 s26, s26, s23
	s_addc_u32 s27, s27, 0
	s_add_u32 s25, s21, 3
	s_lshl_b32 s25, 1, s25
	v_add_u32_e32 v21, s25, v1
	v_add_u32_e32 v22, s25, v21
	v_add_u32_e32 v23, s25, v22
	v_add_u32_e32 v24, s25, v23
	v_add_u32_e32 v25, s25, v24
	v_add_u32_e32 v26, s25, v25
	v_add_u32_e32 v27, s25, v26
	global_load_dword v40, v1, s[26:27]
	global_load_dword v41, v21, s[26:27]
	global_load_dword v42, v22, s[26:27]
	global_load_dword v43, v23, s[26:27]
	global_load_dword v44, v24, s[26:27]
	global_load_dword v45, v25, s[26:27]
	global_load_dword v46, v26, s[26:27]
	global_load_dword v47, v27, s[26:27]
	s_cmp_eq_u32 s7, 1
	s_cbranch_scc1 .Lcve_wA8
	s_waitcnt vmcnt(9)
	s_branch .Lcve_pA

; __device__ __forceinline__ unsigned cvt_pk_bf16(float lo, float hi) { unsigned r; asm volatile("v_cvt_pk_bf16_f32 %0, %1, %2" : "=v"(r) : "v"(lo), "v"(hi)); return r; }
; __device__ __forceinline__ void conv_matrix(const float* __restrict__ src, int K, int N, int Npad, bf16_t* __restrict__ dst, const float* __restrict__ scale, float* tile) {
;     ...
;     __syncthreads();
; #pragma unroll
;     for (int i = 0; i < 8; ++i) { tile[(ty + 8 * i) * 65 + tx] = va[i]; if (has1) tile[4160 + (ty + 8 * i) * 65 + tx] = vb[i]; }
;     __syncthreads();
;     { float v[8];
; #pragma unroll
;       for (int j = 0; j < 8; ++j) v[j] = tile[(ks + j) * 65 + nl];
;       u32x4 w = {cvt_pk_bf16(v[0], v[1]), cvt_pk_bf16(v[2], v[3]), cvt_pk_bf16(v[4], v[5]), cvt_pk_bf16(v[6], v[7])};
;       *(u32x4*)(dst + (size_t)(n0a + nl) * K + k0a + ks) = w; }
;     if (has1) { float v[8];
; #pragma unroll
;       for (int j = 0; j < 8; ++j) v[j] = tile[4160 + (ks + j) * 65 + nl];
;       u32x4 w = {cvt_pk_bf16(v[0], v[1]), cvt_pk_bf16(v[2], v[3]), cvt_pk_bf16(v[4], v[5]), cvt_pk_bf16(v[6], v[7])};
;       *(u32x4*)(dst + (size_t)(n0b + nl) * K + k0b + ks) = w; }
.Lcve_pA:
	s_mov_b32 s7, 0
	ds_write_b32 v2, v30 offset:0
	ds_write_b32 v2, v31 offset:2080
	ds_write_b32 v2, v32 offset:4160
	ds_write_b32 v2, v33 offset:6240
	ds_write_b32 v2, v34 offset:8320
	ds_write_b32 v2, v35 offset:10400
	ds_write_b32 v2, v36 offset:12480
	ds_write_b32 v2, v37 offset:14560
	s_cmp_lt_u32 s4, 0x400
	s_cselect_b32 s20, 4, 6
	s_cselect_b32 s21, 17, 19
	s_cselect_b32 s8, 11, 13
	s_mov_b32 s9, 0x9280000
	s_cselect_b32 s9, 0x8a80000, s9
	s_and_b32 s22, s4, 0x3ff
	s_lshl_b32 s25, 1, s20
	s_sub_u32 s25, s25, 1
	s_and_b32 s23, s22, s25
	s_lshr_b32 s24, s22, s20
	s_lshl_b32 s24, s24, s21
	s_lshl_b32 s23, s23, 7
	s_add_u32 s24, s24, s23
	s_add_u32 s24, s24, s9
	s_add_u32 s26, s14, s24
	s_addc_u32 s27, s15, 0
	v_lshlrev_b32_e32 v6, s8, v4
	v_add_u32_e32 v6, v6, v5
	s_waitcnt lgkmcnt(0)
	s_barrier
	ds_read_b32 v50, v3 offset:0
	ds_read_b32 v51, v3 offset:260
	ds_read_b32 v52, v3 offset:520
	ds_read_b32 v53, v3 offset:780
	ds_read_b32 v54, v3 offset:1040
	ds_read_b32 v55, v3 offset:1300
	ds_read_b32 v56, v3 offset:1560
	ds_read_b32 v57, v3 offset:1820
	s_waitcnt lgkmcnt(0)
	v_cvt_pk_bf16_f32 v60, v50, v51
	v_cvt_pk_bf16_f32 v61, v52, v53
	v_cvt_pk_bf16_f32 v62, v54, v55
	v_cvt_pk_bf16_f32 v63, v56, v57
	global_store_dwordx4 v6, v[60:63], s[26:27]
	s_mov_b32 s4, s5
	s_add_u32 s5, s4, 179
	s_cmp_lt_u32 s5, 0x800
	s_cbranch_scc0 .Lcve_lastB
	s_cmp_lt_u32 s5, 0x400
	s_cselect_b32 s20, 4, 6
	s_cselect_b32 s21, 14, 12
	s_cselect_b32 s26, s10, s12
	s_cselect_b32 s27, s11, s13
	s_and_b32 s22, s5, 0x3ff
	s_lshl_b32 s25, 1, s20
	s_sub_u32 s25, s25, 1
	s_and_b32 s23, s22, s25
	s_lshr_b32 s24, s22, s20
	s_lshl_b32 s23, s23, 6
	s_add_u32 s23, s23, s6
	s_lshl_b32 s23, s23, s21
	s_lshl_b32 s24, s24, 8
	s_add_u32 s23, s23, s24
	s_add_u32 s26, s26, s23
	s_addc_u32 s27, s27, 0
	s_add_u32 s25, s21, 3
	s_lshl_b32 s25, 1, s25
	v_add_u32_e32 v21, s25, v1
	v_add_u32_e32 v22, s25, v21
	v_add_u32_e32 v23, s25, v22
	v_add_u32_e32 v24, s25, v23
	v_add_u32_e32 v25, s25, v24
	v_add_u32_e32 v26, s25, v25
	v_add_u32_e32 v27, s25, v26
	global_load_dword v30, v1, s[26:27]
	global_load_dword v31, v21, s[26:27]
	global_load_dword v32, v22, s[26:27]
	global_load_dword v33, v23, s[26:27]
	global_load_dword v34, v24, s[26:27]
	global_load_dword v35, v25, s[26:27]
	global_load_dword v36, v26, s[26:27]
	global_load_dword v37, v27, s[26:27]
	s_waitcnt vmcnt(9)
	ds_write_b32 v2, v40 offset:16640
	ds_write_b32 v2, v41 offset:18720
	ds_write_b32 v2, v42 offset:20800
	ds_write_b32 v2, v43 offset:22880
	ds_write_b32 v2, v44 offset:24960
	ds_write_b32 v2, v45 offset:27040
	ds_write_b32 v2, v46 offset:29120
	ds_write_b32 v2, v47 offset:31200
	s_cmp_lt_u32 s4, 0x400
	s_cselect_b32 s20, 4, 6
	s_cselect_b32 s21, 17, 19
	s_cselect_b32 s8, 11, 13
	s_mov_b32 s9, 0x9280000
	s_cselect_b32 s9, 0x8a80000, s9
	s_and_b32 s22, s4, 0x3ff
	s_lshl_b32 s25, 1, s20
	s_sub_u32 s25, s25, 1
	s_and_b32 s23, s22, s25
	s_lshr_b32 s24, s22, s20
	s_lshl_b32 s24, s24, s21
	s_lshl_b32 s23, s23, 7
	s_add_u32 s24, s24, s23
	s_add_u32 s24, s24, s9
	s_add_u32 s26, s14, s24
	s_addc_u32 s27, s15, 0
	v_lshlrev_b32_e32 v6, s8, v4
	v_add_u32_e32 v6, v6, v5
	s_waitcnt lgkmcnt(0)
	s_barrier
	ds_read_b32 v50, v3 offset:16640
	ds_read_b32 v51, v3 offset:16900
	ds_read_b32 v52, v3 offset:17160
	ds_read_b32 v53, v3 offset:17420
	ds_read_b32 v54, v3 offset:17680
	ds_read_b32 v55, v3 offset:17940
	ds_read_b32 v56, v3 offset:18200
	ds_read_b32 v57, v3 offset:18460
	s_waitcnt lgkmcnt(0)
	v_cvt_pk_bf16_f32 v60, v50, v51
	v_cvt_pk_bf16_f32 v61, v52, v53
	v_cvt_pk_bf16_f32 v62, v54, v55
	v_cvt_pk_bf16_f32 v63, v56, v57
	global_store_dwordx4 v6, v[60:63], s[26:27]
	s_mov_b32 s4, s5
	s_branch .Lcve_loop
